# P1: the two 8-tile cross-attention K/V GEMMs no longer share CUs 0-7; the V^T GEMM runs on CUs 8-15 concurrently
# speedup vs baseline: 1.0300x; 1.0049x over previous
;     __host__ __device__ bool next(int i, Unit& u) const {
;         const long L = (long)i * G + c; if (L >= nwg) return false;
;         int wgid = (int)L; { const int q = nwg / NXCD, r = nwg % NXCD, xcd = wgid % NXCD, off = wgid / NXCD; wgid = (xcd < r ? xcd * (q + 1) : r * (q + 1) + (xcd - r) * q) + off; }
;         const int nig = WGM * nN, gid = wgid / nig, fm = gid * WGM, gsz = (nM - fm) < WGM ? (nM - fm) : WGM;
;         u.pm = fm + ((wgid % nig) % gsz); u.pn = (wgid % nig) / gsz; return true;
; __global__ void __launch_bounds__(512, 2) mega(Params p_unused) {
;     ...
;             run_gemm(lds, memn, D, WPTR(W_XK), D, 512, 1024, D, EpiRowP{w, WS_MISC + M_KX, 1024, -1, 0.f, 1.f});
;             run_gemm(lds, WPTR(W_XV), D, memn, D, 1024, 512, D, EpiCol{w, WS_MISC + M_VXT, 512, -1, 0.f, 1024});
.LBB0_410:
	v_mov_b32_e32 v14, v224
	s_sub_i32 s5, s2, 8
	s_cmp_lt_u32 s5, 8
	s_cselect_b64 s[6:7], 0, -1
	s_and_b64 vcc, exec, s[6:7]
	v_readfirstlane_b32 s4, v14
	s_cbranch_vccnz .LBB0_412
	s_lshr_b32 s20, s5, 2
	s_and_b32 s22, s5, 3
